# re-measure k17 paired (quick timings drifted)
# baseline (speedup 1.0000x reference)
.LBB0_121:
	v_add_u32_e32 v38, s20, v40
	v_cmp_gt_i32_e64 s[4:5], s3, v38
	v_ashrrev_i32_e32 v39, 31, v38
	s_and_saveexec_b64 s[6:7], s[4:5]
	s_cbranch_execz .LBB0_123
	v_lshlrev_b64 v[2:3], 12, v[38:39]
	s_waitcnt lgkmcnt(0)
	v_lshl_add_u64 v[50:51], v[36:37], 0, v[2:3]
	global_load_dwordx4 v[22:25], v[50:51], off offset:16
	global_load_dwordx4 v[2:5], v[50:51], off
	global_load_dwordx4 v[26:29], v[50:51], off offset:2064
	global_load_dwordx4 v[30:33], v[50:51], off offset:2048
	s_or_b64 exec, exec, s[6:7]
	s_waitcnt vmcnt(4) lgkmcnt(0)
	s_branch .Le00_p0

.Le00_p0:
	v_mul_f32_e32 v41, v7, v7
	v_fmac_f32_e32 v41, v6, v6
	v_fmac_f32_e32 v41, v8, v8
	v_fmac_f32_e32 v41, v9, v9
	v_fmac_f32_e32 v41, v10, v10
	v_fmac_f32_e32 v41, v11, v11
	v_fmac_f32_e32 v41, v12, v12
	v_fmac_f32_e32 v41, v13, v13
	v_fmac_f32_e32 v41, v14, v14
	v_fmac_f32_e32 v41, v15, v15
	v_fmac_f32_e32 v41, v16, v16
	v_fmac_f32_e32 v41, v17, v17
	v_fmac_f32_e32 v41, v18, v18
	v_fmac_f32_e32 v41, v19, v19
	v_fmac_f32_e32 v41, v20, v20
	v_fmac_f32_e32 v41, v21, v21
	ds_bpermute_b32 v49, v42, v41
	v_cvt_pk_bf16_f32 v51, v8, v9
	v_cvt_pk_bf16_f32 v52, v10, v11
	s_waitcnt lgkmcnt(0)
	v_add_f32_e32 v41, v41, v49
	ds_bpermute_b32 v49, v43, v41
	s_waitcnt lgkmcnt(0)
	v_add_f32_e32 v49, v41, v49
	ds_bpermute_b32 v50, v44, v49
	v_ashrrev_i32_e32 v41, 31, v40
	v_lshlrev_b64 v[54:55], 11, v[40:41]
	v_lshl_add_u64 v[56:57], v[34:35], 0, v[54:55]
	v_cvt_pk_bf16_f32 v54, v18, v19
	s_waitcnt lgkmcnt(0)
	v_add_f32_e32 v49, v49, v50
	ds_bpermute_b32 v53, v45, v49
	v_cvt_pk_bf16_f32 v50, v6, v7
	v_cvt_pk_bf16_f32 v55, v20, v21
	s_waitcnt lgkmcnt(0)
	v_add_f32_e32 v49, v49, v53
	ds_bpermute_b32 v58, v46, v49
	v_cvt_pk_bf16_f32 v53, v12, v13
	global_store_dwordx4 v[56:57], v[50:53], off
	s_waitcnt lgkmcnt(0)
	v_add_f32_e32 v49, v49, v58
	ds_bpermute_b32 v50, v47, v49
	v_cvt_pk_bf16_f32 v52, v14, v15
	v_cvt_pk_bf16_f32 v53, v16, v17
	global_store_dwordx4 v[56:57], v[52:55], off offset:1024
	s_and_saveexec_b64 s[14:15], vcc
	s_cbranch_execz .LBB0_125
	s_waitcnt lgkmcnt(0)
	v_add_f32_e32 v49, v49, v50
	v_fmamk_f32 v49, v49, 0x3a800000, v48
	v_mul_f32_e32 v50, 0x4b800000, v49
	v_cmp_gt_f32_e64 s[6:7], s19, v49
	s_nop 1
	v_cndmask_b32_e64 v49, v49, v50, s[6:7]
	v_rsq_f32_e32 v49, v49
	s_nop 0
	v_mul_f32_e32 v50, 0x45800000, v49
	v_cndmask_b32_e64 v49, v49, v50, s[6:7]
	v_lshl_add_u64 v[50:51], v[40:41], 2, s[10:11]
	global_store_dword v[50:51], v49, off
.LBB0_125:
	s_or_b64 exec, exec, s[14:15]
	s_and_saveexec_b64 s[6:7], s[4:5]
	s_cbranch_execz .LBB0_120
	v_add_u32_e32 v40, s18, v40
	v_cmp_gt_i32_e64 s[4:5], s3, v40
	s_and_saveexec_b64 s[14:15], s[4:5]
	s_cbranch_execz .LBB0_128
	v_ashrrev_i32_e32 v41, 31, v40
	v_lshlrev_b64 v[6:7], 12, v[40:41]
	v_lshl_add_u64 v[40:41], v[36:37], 0, v[6:7]
	global_load_dwordx4 v[10:13], v[40:41], off offset:16
	global_load_dwordx4 v[6:9], v[40:41], off
	global_load_dwordx4 v[18:21], v[40:41], off offset:2064
	global_load_dwordx4 v[14:17], v[40:41], off offset:2048
	s_or_b64 exec, exec, s[14:15]
	s_waitcnt vmcnt(4)
	s_branch .Le00_p1
.LBB0_128:
	s_or_b64 exec, exec, s[14:15]
	s_waitcnt vmcnt(0)
.Le00_p1:
	v_mul_f32_e32 v40, v3, v3
	v_fmac_f32_e32 v40, v2, v2
	v_fmac_f32_e32 v40, v4, v4
	v_fmac_f32_e32 v40, v5, v5
	v_fmac_f32_e32 v40, v22, v22
	v_fmac_f32_e32 v40, v23, v23
	v_fmac_f32_e32 v40, v24, v24
	v_fmac_f32_e32 v40, v25, v25
	v_fmac_f32_e32 v40, v30, v30
	v_fmac_f32_e32 v40, v31, v31
	v_fmac_f32_e32 v40, v32, v32
	v_fmac_f32_e32 v40, v33, v33
	v_fmac_f32_e32 v40, v26, v26
	v_fmac_f32_e32 v40, v27, v27
	v_fmac_f32_e32 v40, v28, v28
	v_fmac_f32_e32 v40, v29, v29
	ds_bpermute_b32 v41, v42, v40
	s_waitcnt lgkmcnt(1)
	v_cvt_pk_bf16_f32 v50, v2, v3
	v_cvt_pk_bf16_f32 v51, v4, v5
	v_cvt_pk_bf16_f32 v52, v22, v23
	s_waitcnt lgkmcnt(0)
	v_add_f32_e32 v40, v40, v41
	ds_bpermute_b32 v41, v43, v40
	s_waitcnt lgkmcnt(0)
	v_add_f32_e32 v40, v40, v41
	ds_bpermute_b32 v41, v44, v40
	s_waitcnt lgkmcnt(0)
	v_add_f32_e32 v49, v40, v41
	ds_bpermute_b32 v53, v45, v49
	v_lshlrev_b64 v[40:41], 11, v[38:39]
	v_lshl_add_u64 v[54:55], v[34:35], 0, v[40:41]
	s_waitcnt lgkmcnt(0)
	v_add_f32_e32 v49, v49, v53
	ds_bpermute_b32 v56, v46, v49
	v_cvt_pk_bf16_f32 v53, v24, v25
	global_store_dwordx4 v[54:55], v[50:53], off
	s_waitcnt lgkmcnt(0)
	v_add_f32_e32 v40, v49, v56
	ds_bpermute_b32 v41, v47, v40
	v_cvt_pk_bf16_f32 v50, v30, v31
	v_cvt_pk_bf16_f32 v51, v32, v33
	v_cvt_pk_bf16_f32 v52, v26, v27
	v_cvt_pk_bf16_f32 v53, v28, v29
	global_store_dwordx4 v[54:55], v[50:53], off offset:1024
	s_and_saveexec_b64 s[14:15], vcc
	s_cbranch_execz .LBB0_119
	s_waitcnt lgkmcnt(0)
	v_add_f32_e32 v40, v40, v41
	v_fmamk_f32 v40, v40, 0x3a800000, v48
	v_mul_f32_e32 v41, 0x4b800000, v40
	v_cmp_gt_f32_e64 s[4:5], s19, v40
	s_nop 1
	v_cndmask_b32_e64 v40, v40, v41, s[4:5]
	v_rsq_f32_e32 v40, v40
	s_nop 0
	v_mul_f32_e32 v41, 0x45800000, v40
	v_cndmask_b32_e64 v49, v40, v41, s[4:5]
	v_lshl_add_u64 v[40:41], v[38:39], 2, s[10:11]
	global_store_dword v[40:41], v49, off
	s_branch .LBB0_119
